# P8 sample unit: K-score phase rewritten by hand (6 row groups of K in flight per wave instead of one, DPP row sums instead of 16 serial ds_bpermute hops)
# speedup vs baseline: 1.0326x; 1.0064x over previous
.LBB0_1028:
	s_lshl_b32 s14, s36, 8
	s_and_b32 s24, s36, -4
	s_and_b32 s37, s14, 0x300
	s_add_i32 s22, s24, 0x4000
	s_lshl_b32 s14, s37, 1
	s_ashr_i32 s23, s22, 31
	s_ashr_i32 s25, s24, 31
	v_lshl_add_u64 v[0:1], v[138:139], 0, s[14:15]
	s_lshl_b64 s[26:27], s[22:23], 11
	s_lshl_b64 s[24:25], s[24:25], 11
	v_lshl_add_u64 v[2:3], v[0:1], 0, s[26:27]
	v_lshl_add_u64 v[0:1], v[0:1], 0, s[24:25]
	v_add_co_u32_e32 v10, vcc, s31, v0
	v_lshl_add_u64 v[12:13], v[0:1], 0, s[16:17]
	s_nop 0
	v_addc_co_u32_e32 v11, vcc, 0, v1, vcc
	v_add_co_u32_e32 v18, vcc, s34, v0
	v_lshl_add_u64 v[22:23], v[0:1], 0, s[18:19]
	s_nop 0
	v_addc_co_u32_e32 v19, vcc, 0, v1, vcc
	v_lshl_add_u64 v[0:1], v[0:1], 0, s[20:21]
	global_load_dwordx2 v[4:5], v[2:3], off
	global_load_dwordx2 v[6:7], v[2:3], off offset:128
	global_load_dwordx2 v[8:9], v[2:3], off offset:256
	s_ashr_i32 s24, s36, 2
	global_load_dwordx2 v[10:11], v[10:11], off offset:2048
	s_lshl_b32 s14, s3, 2
	global_load_dwordx2 v[2:3], v[2:3], off offset:384
	s_nop 0
	global_load_dwordx2 v[14:15], v[12:13], off offset:128
	global_load_dwordx2 v[16:17], v[12:13], off offset:256
	s_nop 0
	global_load_dwordx2 v[12:13], v[12:13], off offset:384
	s_ashr_i32 s25, s24, 31
	global_load_dwordx2 v[20:21], v[18:19], off
	global_load_dwordx2 v[62:63], v[22:23], off offset:128
	global_load_dwordx2 v[66:67], v[22:23], off offset:256
	s_nop 0
	global_load_dwordx2 v[22:23], v[22:23], off offset:384
	s_nop 0
	global_load_dwordx2 v[18:19], v[18:19], off offset:2048
	s_nop 0
	global_load_dwordx2 v[78:79], v[0:1], off offset:128
	global_load_dwordx2 v[82:83], v[0:1], off offset:256
	s_nop 0
	global_load_dwordx2 v[0:1], v[0:1], off offset:384
	s_and_b32 s14, s14, 0xc00
	s_lshl_b64 s[24:25], s[24:25], 20
	s_or_b32 s26, s24, s14
	s_mov_b32 s27, s25
	v_mov_b32_e32 v88, v203
	s_waitcnt vmcnt(0)
	s_barrier
	v_lshlrev_b32_e32 v24, 16, v4
	v_and_b32_e32 v25, 0xffff0000, v4
	v_lshlrev_b32_e32 v26, 16, v5
	v_and_b32_e32 v27, 0xffff0000, v5
	v_lshlrev_b32_e32 v28, 16, v6
	v_and_b32_e32 v29, 0xffff0000, v6
	v_lshlrev_b32_e32 v30, 16, v7
	v_and_b32_e32 v31, 0xffff0000, v7
	v_lshlrev_b32_e32 v32, 16, v8
	v_and_b32_e32 v33, 0xffff0000, v8
	v_lshlrev_b32_e32 v34, 16, v9
	v_and_b32_e32 v35, 0xffff0000, v9
	v_lshlrev_b32_e32 v36, 16, v2
	v_and_b32_e32 v37, 0xffff0000, v2
	v_lshlrev_b32_e32 v38, 16, v3
	v_and_b32_e32 v39, 0xffff0000, v3
	v_lshlrev_b32_e32 v40, 16, v10
	v_and_b32_e32 v41, 0xffff0000, v10
	v_lshlrev_b32_e32 v42, 16, v11
	v_and_b32_e32 v43, 0xffff0000, v11
	v_lshlrev_b32_e32 v44, 16, v14
	v_and_b32_e32 v45, 0xffff0000, v14
	v_lshlrev_b32_e32 v46, 16, v15
	v_and_b32_e32 v47, 0xffff0000, v15
	v_lshlrev_b32_e32 v48, 16, v16
	v_and_b32_e32 v49, 0xffff0000, v16
	v_lshlrev_b32_e32 v50, 16, v17
	v_and_b32_e32 v51, 0xffff0000, v17
	v_lshlrev_b32_e32 v52, 16, v12
	v_and_b32_e32 v53, 0xffff0000, v12
	v_lshlrev_b32_e32 v54, 16, v13
	v_and_b32_e32 v55, 0xffff0000, v13
	v_lshlrev_b32_e32 v56, 16, v20
	v_and_b32_e32 v57, 0xffff0000, v20
	v_lshlrev_b32_e32 v58, 16, v21
	v_and_b32_e32 v59, 0xffff0000, v21
	v_lshlrev_b32_e32 v60, 16, v62
	v_and_b32_e32 v61, 0xffff0000, v62
	v_lshlrev_b32_e32 v62, 16, v63
	v_and_b32_e32 v63, 0xffff0000, v63
	v_lshlrev_b32_e32 v64, 16, v66
	v_and_b32_e32 v65, 0xffff0000, v66
	v_lshlrev_b32_e32 v66, 16, v67
	v_and_b32_e32 v67, 0xffff0000, v67
	v_lshlrev_b32_e32 v68, 16, v22
	v_and_b32_e32 v69, 0xffff0000, v22
	v_lshlrev_b32_e32 v70, 16, v23
	v_and_b32_e32 v71, 0xffff0000, v23
	v_lshlrev_b32_e32 v72, 16, v18
	v_and_b32_e32 v73, 0xffff0000, v18
	v_lshlrev_b32_e32 v74, 16, v19
	v_and_b32_e32 v75, 0xffff0000, v19
	v_lshlrev_b32_e32 v76, 16, v78
	v_and_b32_e32 v77, 0xffff0000, v78
	v_lshlrev_b32_e32 v78, 16, v79
	v_and_b32_e32 v79, 0xffff0000, v79
	v_lshlrev_b32_e32 v80, 16, v82
	v_and_b32_e32 v81, 0xffff0000, v82
	v_lshlrev_b32_e32 v82, 16, v83
	v_and_b32_e32 v83, 0xffff0000, v83
	v_lshlrev_b32_e32 v84, 16, v0
	v_and_b32_e32 v85, 0xffff0000, v0
	v_lshlrev_b32_e32 v86, 16, v1
	v_and_b32_e32 v87, 0xffff0000, v1
	v_lshl_add_u64 v[16:17], v[142:143], 0, s[26:27]
	s_mov_b32 s32, 0x4000
	s_mov_b32 s33, 0
	global_load_dwordx4 v[0:3], v[16:17], off nt
	global_load_dwordx4 v[4:7], v[16:17], off offset:256 nt
	global_load_dwordx4 v[8:11], v[16:17], off offset:512 nt
	global_load_dwordx4 v[12:15], v[16:17], off offset:768 nt
	v_lshl_add_u64 v[16:17], v[16:17], 0, s[32:33]
	global_load_dwordx4 v[96:99], v[16:17], off nt
	global_load_dwordx4 v[100:103], v[16:17], off offset:256 nt
	global_load_dwordx4 v[104:107], v[16:17], off offset:512 nt
	global_load_dwordx4 v[108:111], v[16:17], off offset:768 nt
	v_lshl_add_u64 v[16:17], v[16:17], 0, s[32:33]
	global_load_dwordx4 v[112:115], v[16:17], off nt
	global_load_dwordx4 v[116:119], v[16:17], off offset:256 nt
	global_load_dwordx4 v[120:123], v[16:17], off offset:512 nt
	global_load_dwordx4 v[124:127], v[16:17], off offset:768 nt
	v_lshl_add_u64 v[16:17], v[16:17], 0, s[32:33]
	global_load_dwordx4 v[208:211], v[16:17], off nt
	global_load_dwordx4 v[212:215], v[16:17], off offset:256 nt
	global_load_dwordx4 v[216:219], v[16:17], off offset:512 nt
	global_load_dwordx4 v[220:223], v[16:17], off offset:768 nt
	v_lshl_add_u64 v[16:17], v[16:17], 0, s[32:33]
	global_load_dwordx4 v[224:227], v[16:17], off nt
	global_load_dwordx4 v[228:231], v[16:17], off offset:256 nt
	global_load_dwordx4 v[232:235], v[16:17], off offset:512 nt
	global_load_dwordx4 v[236:239], v[16:17], off offset:768 nt
	v_lshl_add_u64 v[16:17], v[16:17], 0, s[32:33]
	global_load_dwordx4 v[240:243], v[16:17], off nt
	global_load_dwordx4 v[244:247], v[16:17], off offset:256 nt
	global_load_dwordx4 v[248:251], v[16:17], off offset:512 nt
	global_load_dwordx4 v[128:131], v[16:17], off offset:768 nt
	v_lshl_add_u64 v[16:17], v[16:17], 0, s[32:33]
	s_waitcnt vmcnt(20)
	v_mul_f32_e32 v89, v1, v25
	v_fmac_f32_e32 v89, v0, v24
	v_fmac_f32_e32 v89, v2, v26
	v_fmac_f32_e32 v89, v3, v27
	v_mul_f32_e32 v93, v5, v29
	v_fmac_f32_e32 v93, v4, v28
	v_fmac_f32_e32 v93, v6, v30
	v_fmac_f32_e32 v93, v7, v31
	v_add_f32_e32 v89, v89, v93
	v_mul_f32_e32 v93, v9, v33
	v_fmac_f32_e32 v93, v8, v32
	v_fmac_f32_e32 v93, v10, v34
	v_fmac_f32_e32 v93, v11, v35
	v_add_f32_e32 v89, v89, v93
	v_mul_f32_e32 v93, v13, v37
	v_fmac_f32_e32 v93, v12, v36
	v_fmac_f32_e32 v93, v14, v38
	v_fmac_f32_e32 v93, v15, v39
	v_add_f32_e32 v89, v89, v93
	v_mul_f32_e32 v90, v1, v41
	v_fmac_f32_e32 v90, v0, v40
	v_fmac_f32_e32 v90, v2, v42
	v_fmac_f32_e32 v90, v3, v43
	v_mul_f32_e32 v93, v5, v45
	v_fmac_f32_e32 v93, v4, v44
	v_fmac_f32_e32 v93, v6, v46
	v_fmac_f32_e32 v93, v7, v47
	v_add_f32_e32 v90, v90, v93
	v_mul_f32_e32 v93, v9, v49
	v_fmac_f32_e32 v93, v8, v48
	v_fmac_f32_e32 v93, v10, v50
	v_fmac_f32_e32 v93, v11, v51
	v_add_f32_e32 v90, v90, v93
	v_mul_f32_e32 v93, v13, v53
	v_fmac_f32_e32 v93, v12, v52
	v_fmac_f32_e32 v93, v14, v54
	v_fmac_f32_e32 v93, v15, v55
	v_add_f32_e32 v90, v90, v93
	v_mul_f32_e32 v91, v1, v57
	v_fmac_f32_e32 v91, v0, v56
	v_fmac_f32_e32 v91, v2, v58
	v_fmac_f32_e32 v91, v3, v59
	v_mul_f32_e32 v93, v5, v61
	v_fmac_f32_e32 v93, v4, v60
	v_fmac_f32_e32 v93, v6, v62
	v_fmac_f32_e32 v93, v7, v63
	v_add_f32_e32 v91, v91, v93
	v_mul_f32_e32 v93, v9, v65
	v_fmac_f32_e32 v93, v8, v64
	v_fmac_f32_e32 v93, v10, v66
	v_fmac_f32_e32 v93, v11, v67
	v_add_f32_e32 v91, v91, v93
	v_mul_f32_e32 v93, v13, v69
	v_fmac_f32_e32 v93, v12, v68
	v_fmac_f32_e32 v93, v14, v70
	v_fmac_f32_e32 v93, v15, v71
	v_add_f32_e32 v91, v91, v93
	v_mul_f32_e32 v92, v1, v73
	v_fmac_f32_e32 v92, v0, v72
	v_fmac_f32_e32 v92, v2, v74
	v_fmac_f32_e32 v92, v3, v75
	v_mul_f32_e32 v93, v5, v77
	v_fmac_f32_e32 v93, v4, v76
	v_fmac_f32_e32 v93, v6, v78
	v_fmac_f32_e32 v93, v7, v79
	v_add_f32_e32 v92, v92, v93
	v_mul_f32_e32 v93, v9, v81
	v_fmac_f32_e32 v93, v8, v80
	v_fmac_f32_e32 v93, v10, v82
	v_fmac_f32_e32 v93, v11, v83
	v_add_f32_e32 v92, v92, v93
	v_mul_f32_e32 v93, v13, v85
	v_fmac_f32_e32 v93, v12, v84
	v_fmac_f32_e32 v93, v14, v86
	v_fmac_f32_e32 v93, v15, v87
	v_add_f32_e32 v92, v92, v93
	global_load_dwordx4 v[0:3], v[16:17], off nt
	global_load_dwordx4 v[4:7], v[16:17], off offset:256 nt
	global_load_dwordx4 v[8:11], v[16:17], off offset:512 nt
	global_load_dwordx4 v[12:15], v[16:17], off offset:768 nt
	v_lshl_add_u64 v[16:17], v[16:17], 0, s[32:33]
	v_add_f32_dpp v89, v89, v89 quad_perm:[1,0,3,2] row_mask:0xf bank_mask:0xf
	v_add_f32_dpp v90, v90, v90 quad_perm:[1,0,3,2] row_mask:0xf bank_mask:0xf
	v_add_f32_dpp v91, v91, v91 quad_perm:[1,0,3,2] row_mask:0xf bank_mask:0xf
	v_add_f32_dpp v92, v92, v92 quad_perm:[1,0,3,2] row_mask:0xf bank_mask:0xf
	v_add_f32_dpp v89, v89, v89 quad_perm:[2,3,0,1] row_mask:0xf bank_mask:0xf
	v_add_f32_dpp v90, v90, v90 quad_perm:[2,3,0,1] row_mask:0xf bank_mask:0xf
	v_add_f32_dpp v91, v91, v91 quad_perm:[2,3,0,1] row_mask:0xf bank_mask:0xf
	v_add_f32_dpp v92, v92, v92 quad_perm:[2,3,0,1] row_mask:0xf bank_mask:0xf
	v_add_f32_dpp v89, v89, v89 row_half_mirror row_mask:0xf bank_mask:0xf
	v_add_f32_dpp v90, v90, v90 row_half_mirror row_mask:0xf bank_mask:0xf
	v_add_f32_dpp v91, v91, v91 row_half_mirror row_mask:0xf bank_mask:0xf
	v_add_f32_dpp v92, v92, v92 row_half_mirror row_mask:0xf bank_mask:0xf
	v_add_f32_dpp v89, v89, v89 row_mirror row_mask:0xf bank_mask:0xf
	v_add_f32_dpp v90, v90, v90 row_mirror row_mask:0xf bank_mask:0xf
	v_add_f32_dpp v91, v91, v91 row_mirror row_mask:0xf bank_mask:0xf
	v_add_f32_dpp v92, v92, v92 row_mirror row_mask:0xf bank_mask:0xf
	v_mul_f32_e32 v89, 0x3d800000, v89
	v_mul_f32_e32 v90, 0x3d800000, v90
	v_mul_f32_e32 v91, 0x3d800000, v91
	v_mul_f32_e32 v92, 0x3d800000, v92
	s_and_saveexec_b64 s[28:29], s[0:1]
	ds_write_b32 v88, v89
	ds_write_b32 v88, v90 offset:1024
	ds_write_b32 v88, v91 offset:2048
	ds_write_b32 v88, v92 offset:3072
	s_mov_b64 exec, s[28:29]
	s_waitcnt vmcnt(20)
	v_mul_f32_e32 v89, v97, v25
	v_fmac_f32_e32 v89, v96, v24
	v_fmac_f32_e32 v89, v98, v26
	v_fmac_f32_e32 v89, v99, v27
	v_mul_f32_e32 v93, v101, v29
	v_fmac_f32_e32 v93, v100, v28
	v_fmac_f32_e32 v93, v102, v30
	v_fmac_f32_e32 v93, v103, v31
	v_add_f32_e32 v89, v89, v93
	v_mul_f32_e32 v93, v105, v33
	v_fmac_f32_e32 v93, v104, v32
	v_fmac_f32_e32 v93, v106, v34
	v_fmac_f32_e32 v93, v107, v35
	v_add_f32_e32 v89, v89, v93
	v_mul_f32_e32 v93, v109, v37
	v_fmac_f32_e32 v93, v108, v36
	v_fmac_f32_e32 v93, v110, v38
	v_fmac_f32_e32 v93, v111, v39
	v_add_f32_e32 v89, v89, v93
	v_mul_f32_e32 v90, v97, v41
	v_fmac_f32_e32 v90, v96, v40
	v_fmac_f32_e32 v90, v98, v42
	v_fmac_f32_e32 v90, v99, v43
	v_mul_f32_e32 v93, v101, v45
	v_fmac_f32_e32 v93, v100, v44
	v_fmac_f32_e32 v93, v102, v46
	v_fmac_f32_e32 v93, v103, v47
	v_add_f32_e32 v90, v90, v93
	v_mul_f32_e32 v93, v105, v49
	v_fmac_f32_e32 v93, v104, v48
	v_fmac_f32_e32 v93, v106, v50
	v_fmac_f32_e32 v93, v107, v51
	v_add_f32_e32 v90, v90, v93
	v_mul_f32_e32 v93, v109, v53
	v_fmac_f32_e32 v93, v108, v52
	v_fmac_f32_e32 v93, v110, v54
	v_fmac_f32_e32 v93, v111, v55
	v_add_f32_e32 v90, v90, v93
	v_mul_f32_e32 v91, v97, v57
	v_fmac_f32_e32 v91, v96, v56
	v_fmac_f32_e32 v91, v98, v58
	v_fmac_f32_e32 v91, v99, v59
	v_mul_f32_e32 v93, v101, v61
	v_fmac_f32_e32 v93, v100, v60
	v_fmac_f32_e32 v93, v102, v62
	v_fmac_f32_e32 v93, v103, v63
	v_add_f32_e32 v91, v91, v93
	v_mul_f32_e32 v93, v105, v65
	v_fmac_f32_e32 v93, v104, v64
	v_fmac_f32_e32 v93, v106, v66
	v_fmac_f32_e32 v93, v107, v67
	v_add_f32_e32 v91, v91, v93
	v_mul_f32_e32 v93, v109, v69
	v_fmac_f32_e32 v93, v108, v68
	v_fmac_f32_e32 v93, v110, v70
	v_fmac_f32_e32 v93, v111, v71
	v_add_f32_e32 v91, v91, v93
	v_mul_f32_e32 v92, v97, v73
	v_fmac_f32_e32 v92, v96, v72
	v_fmac_f32_e32 v92, v98, v74
	v_fmac_f32_e32 v92, v99, v75
	v_mul_f32_e32 v93, v101, v77
	v_fmac_f32_e32 v93, v100, v76
	v_fmac_f32_e32 v93, v102, v78
	v_fmac_f32_e32 v93, v103, v79
	v_add_f32_e32 v92, v92, v93
	v_mul_f32_e32 v93, v105, v81
	v_fmac_f32_e32 v93, v104, v80
	v_fmac_f32_e32 v93, v106, v82
	v_fmac_f32_e32 v93, v107, v83
	v_add_f32_e32 v92, v92, v93
	v_mul_f32_e32 v93, v109, v85
	v_fmac_f32_e32 v93, v108, v84
	v_fmac_f32_e32 v93, v110, v86
	v_fmac_f32_e32 v93, v111, v87
	v_add_f32_e32 v92, v92, v93
	global_load_dwordx4 v[96:99], v[16:17], off nt
	global_load_dwordx4 v[100:103], v[16:17], off offset:256 nt
	global_load_dwordx4 v[104:107], v[16:17], off offset:512 nt
	global_load_dwordx4 v[108:111], v[16:17], off offset:768 nt
	v_lshl_add_u64 v[16:17], v[16:17], 0, s[32:33]
	v_add_f32_dpp v89, v89, v89 quad_perm:[1,0,3,2] row_mask:0xf bank_mask:0xf
	v_add_f32_dpp v90, v90, v90 quad_perm:[1,0,3,2] row_mask:0xf bank_mask:0xf
	v_add_f32_dpp v91, v91, v91 quad_perm:[1,0,3,2] row_mask:0xf bank_mask:0xf
	v_add_f32_dpp v92, v92, v92 quad_perm:[1,0,3,2] row_mask:0xf bank_mask:0xf
	v_add_f32_dpp v89, v89, v89 quad_perm:[2,3,0,1] row_mask:0xf bank_mask:0xf
	v_add_f32_dpp v90, v90, v90 quad_perm:[2,3,0,1] row_mask:0xf bank_mask:0xf
	v_add_f32_dpp v91, v91, v91 quad_perm:[2,3,0,1] row_mask:0xf bank_mask:0xf
	v_add_f32_dpp v92, v92, v92 quad_perm:[2,3,0,1] row_mask:0xf bank_mask:0xf
	v_add_f32_dpp v89, v89, v89 row_half_mirror row_mask:0xf bank_mask:0xf
	v_add_f32_dpp v90, v90, v90 row_half_mirror row_mask:0xf bank_mask:0xf
	v_add_f32_dpp v91, v91, v91 row_half_mirror row_mask:0xf bank_mask:0xf
	v_add_f32_dpp v92, v92, v92 row_half_mirror row_mask:0xf bank_mask:0xf
	v_add_f32_dpp v89, v89, v89 row_mirror row_mask:0xf bank_mask:0xf
	v_add_f32_dpp v90, v90, v90 row_mirror row_mask:0xf bank_mask:0xf
	v_add_f32_dpp v91, v91, v91 row_mirror row_mask:0xf bank_mask:0xf
	v_add_f32_dpp v92, v92, v92 row_mirror row_mask:0xf bank_mask:0xf
	v_mul_f32_e32 v89, 0x3d800000, v89
	v_mul_f32_e32 v90, 0x3d800000, v90
	v_mul_f32_e32 v91, 0x3d800000, v91
	v_mul_f32_e32 v92, 0x3d800000, v92
	s_and_saveexec_b64 s[28:29], s[0:1]
	ds_write_b32 v88, v89 offset:16
	ds_write_b32 v88, v90 offset:1040
	ds_write_b32 v88, v91 offset:2064
	ds_write_b32 v88, v92 offset:3088
	s_mov_b64 exec, s[28:29]
	s_waitcnt vmcnt(20)
	v_mul_f32_e32 v89, v113, v25
	v_fmac_f32_e32 v89, v112, v24
	v_fmac_f32_e32 v89, v114, v26
	v_fmac_f32_e32 v89, v115, v27
	v_mul_f32_e32 v93, v117, v29
	v_fmac_f32_e32 v93, v116, v28
	v_fmac_f32_e32 v93, v118, v30
	v_fmac_f32_e32 v93, v119, v31
	v_add_f32_e32 v89, v89, v93
	v_mul_f32_e32 v93, v121, v33
	v_fmac_f32_e32 v93, v120, v32
	v_fmac_f32_e32 v93, v122, v34
	v_fmac_f32_e32 v93, v123, v35
	v_add_f32_e32 v89, v89, v93
	v_mul_f32_e32 v93, v125, v37
	v_fmac_f32_e32 v93, v124, v36
	v_fmac_f32_e32 v93, v126, v38
	v_fmac_f32_e32 v93, v127, v39
	v_add_f32_e32 v89, v89, v93
	v_mul_f32_e32 v90, v113, v41
	v_fmac_f32_e32 v90, v112, v40
	v_fmac_f32_e32 v90, v114, v42
	v_fmac_f32_e32 v90, v115, v43
	v_mul_f32_e32 v93, v117, v45
	v_fmac_f32_e32 v93, v116, v44
	v_fmac_f32_e32 v93, v118, v46
	v_fmac_f32_e32 v93, v119, v47
	v_add_f32_e32 v90, v90, v93
	v_mul_f32_e32 v93, v121, v49
	v_fmac_f32_e32 v93, v120, v48
	v_fmac_f32_e32 v93, v122, v50
	v_fmac_f32_e32 v93, v123, v51
	v_add_f32_e32 v90, v90, v93
	v_mul_f32_e32 v93, v125, v53
	v_fmac_f32_e32 v93, v124, v52
	v_fmac_f32_e32 v93, v126, v54
	v_fmac_f32_e32 v93, v127, v55
	v_add_f32_e32 v90, v90, v93
	v_mul_f32_e32 v91, v113, v57
	v_fmac_f32_e32 v91, v112, v56
	v_fmac_f32_e32 v91, v114, v58
	v_fmac_f32_e32 v91, v115, v59
	v_mul_f32_e32 v93, v117, v61
	v_fmac_f32_e32 v93, v116, v60
	v_fmac_f32_e32 v93, v118, v62
	v_fmac_f32_e32 v93, v119, v63
	v_add_f32_e32 v91, v91, v93
	v_mul_f32_e32 v93, v121, v65
	v_fmac_f32_e32 v93, v120, v64
	v_fmac_f32_e32 v93, v122, v66
	v_fmac_f32_e32 v93, v123, v67
	v_add_f32_e32 v91, v91, v93
	v_mul_f32_e32 v93, v125, v69
	v_fmac_f32_e32 v93, v124, v68
	v_fmac_f32_e32 v93, v126, v70
	v_fmac_f32_e32 v93, v127, v71
	v_add_f32_e32 v91, v91, v93
	v_mul_f32_e32 v92, v113, v73
	v_fmac_f32_e32 v92, v112, v72
	v_fmac_f32_e32 v92, v114, v74
	v_fmac_f32_e32 v92, v115, v75
	v_mul_f32_e32 v93, v117, v77
	v_fmac_f32_e32 v93, v116, v76
	v_fmac_f32_e32 v93, v118, v78
	v_fmac_f32_e32 v93, v119, v79
	v_add_f32_e32 v92, v92, v93
	v_mul_f32_e32 v93, v121, v81
	v_fmac_f32_e32 v93, v120, v80
	v_fmac_f32_e32 v93, v122, v82
	v_fmac_f32_e32 v93, v123, v83
	v_add_f32_e32 v92, v92, v93
	v_mul_f32_e32 v93, v125, v85
	v_fmac_f32_e32 v93, v124, v84
	v_fmac_f32_e32 v93, v126, v86
	v_fmac_f32_e32 v93, v127, v87
	v_add_f32_e32 v92, v92, v93
	v_add_f32_dpp v89, v89, v89 quad_perm:[1,0,3,2] row_mask:0xf bank_mask:0xf
	v_add_f32_dpp v90, v90, v90 quad_perm:[1,0,3,2] row_mask:0xf bank_mask:0xf
	v_add_f32_dpp v91, v91, v91 quad_perm:[1,0,3,2] row_mask:0xf bank_mask:0xf
	v_add_f32_dpp v92, v92, v92 quad_perm:[1,0,3,2] row_mask:0xf bank_mask:0xf
	v_add_f32_dpp v89, v89, v89 quad_perm:[2,3,0,1] row_mask:0xf bank_mask:0xf
	v_add_f32_dpp v90, v90, v90 quad_perm:[2,3,0,1] row_mask:0xf bank_mask:0xf
	v_add_f32_dpp v91, v91, v91 quad_perm:[2,3,0,1] row_mask:0xf bank_mask:0xf
	v_add_f32_dpp v92, v92, v92 quad_perm:[2,3,0,1] row_mask:0xf bank_mask:0xf
	v_add_f32_dpp v89, v89, v89 row_half_mirror row_mask:0xf bank_mask:0xf
	v_add_f32_dpp v90, v90, v90 row_half_mirror row_mask:0xf bank_mask:0xf
	v_add_f32_dpp v91, v91, v91 row_half_mirror row_mask:0xf bank_mask:0xf
	v_add_f32_dpp v92, v92, v92 row_half_mirror row_mask:0xf bank_mask:0xf
	v_add_f32_dpp v89, v89, v89 row_mirror row_mask:0xf bank_mask:0xf
	v_add_f32_dpp v90, v90, v90 row_mirror row_mask:0xf bank_mask:0xf
	v_add_f32_dpp v91, v91, v91 row_mirror row_mask:0xf bank_mask:0xf
	v_add_f32_dpp v92, v92, v92 row_mirror row_mask:0xf bank_mask:0xf
	v_mul_f32_e32 v89, 0x3d800000, v89
	v_mul_f32_e32 v90, 0x3d800000, v90
	v_mul_f32_e32 v91, 0x3d800000, v91
	v_mul_f32_e32 v92, 0x3d800000, v92
	s_and_saveexec_b64 s[28:29], s[0:1]
	ds_write_b32 v88, v89 offset:32
	ds_write_b32 v88, v90 offset:1056
	ds_write_b32 v88, v91 offset:2080
	ds_write_b32 v88, v92 offset:3104
	s_mov_b64 exec, s[28:29]
	s_waitcnt vmcnt(16)
	v_mul_f32_e32 v89, v209, v25
	v_fmac_f32_e32 v89, v208, v24
	v_fmac_f32_e32 v89, v210, v26
	v_fmac_f32_e32 v89, v211, v27
	v_mul_f32_e32 v93, v213, v29
	v_fmac_f32_e32 v93, v212, v28
	v_fmac_f32_e32 v93, v214, v30
	v_fmac_f32_e32 v93, v215, v31
	v_add_f32_e32 v89, v89, v93
	v_mul_f32_e32 v93, v217, v33
	v_fmac_f32_e32 v93, v216, v32
	v_fmac_f32_e32 v93, v218, v34
	v_fmac_f32_e32 v93, v219, v35
	v_add_f32_e32 v89, v89, v93
	v_mul_f32_e32 v93, v221, v37
	v_fmac_f32_e32 v93, v220, v36
	v_fmac_f32_e32 v93, v222, v38
	v_fmac_f32_e32 v93, v223, v39
	v_add_f32_e32 v89, v89, v93
	v_mul_f32_e32 v90, v209, v41
	v_fmac_f32_e32 v90, v208, v40
	v_fmac_f32_e32 v90, v210, v42
	v_fmac_f32_e32 v90, v211, v43
	v_mul_f32_e32 v93, v213, v45
	v_fmac_f32_e32 v93, v212, v44
	v_fmac_f32_e32 v93, v214, v46
	v_fmac_f32_e32 v93, v215, v47
	v_add_f32_e32 v90, v90, v93
	v_mul_f32_e32 v93, v217, v49
	v_fmac_f32_e32 v93, v216, v48
	v_fmac_f32_e32 v93, v218, v50
	v_fmac_f32_e32 v93, v219, v51
	v_add_f32_e32 v90, v90, v93
	v_mul_f32_e32 v93, v221, v53
	v_fmac_f32_e32 v93, v220, v52
	v_fmac_f32_e32 v93, v222, v54
	v_fmac_f32_e32 v93, v223, v55
	v_add_f32_e32 v90, v90, v93
	v_mul_f32_e32 v91, v209, v57
	v_fmac_f32_e32 v91, v208, v56
	v_fmac_f32_e32 v91, v210, v58
	v_fmac_f32_e32 v91, v211, v59
	v_mul_f32_e32 v93, v213, v61
	v_fmac_f32_e32 v93, v212, v60
	v_fmac_f32_e32 v93, v214, v62
	v_fmac_f32_e32 v93, v215, v63
	v_add_f32_e32 v91, v91, v93
	v_mul_f32_e32 v93, v217, v65
	v_fmac_f32_e32 v93, v216, v64
	v_fmac_f32_e32 v93, v218, v66
	v_fmac_f32_e32 v93, v219, v67
	v_add_f32_e32 v91, v91, v93
	v_mul_f32_e32 v93, v221, v69
	v_fmac_f32_e32 v93, v220, v68
	v_fmac_f32_e32 v93, v222, v70
	v_fmac_f32_e32 v93, v223, v71
	v_add_f32_e32 v91, v91, v93
	v_mul_f32_e32 v92, v209, v73
	v_fmac_f32_e32 v92, v208, v72
	v_fmac_f32_e32 v92, v210, v74
	v_fmac_f32_e32 v92, v211, v75
	v_mul_f32_e32 v93, v213, v77
	v_fmac_f32_e32 v93, v212, v76
	v_fmac_f32_e32 v93, v214, v78
	v_fmac_f32_e32 v93, v215, v79
	v_add_f32_e32 v92, v92, v93
	v_mul_f32_e32 v93, v217, v81
	v_fmac_f32_e32 v93, v216, v80
	v_fmac_f32_e32 v93, v218, v82
	v_fmac_f32_e32 v93, v219, v83
	v_add_f32_e32 v92, v92, v93
	v_mul_f32_e32 v93, v221, v85
	v_fmac_f32_e32 v93, v220, v84
	v_fmac_f32_e32 v93, v222, v86
	v_fmac_f32_e32 v93, v223, v87
	v_add_f32_e32 v92, v92, v93
	v_add_f32_dpp v89, v89, v89 quad_perm:[1,0,3,2] row_mask:0xf bank_mask:0xf
	v_add_f32_dpp v90, v90, v90 quad_perm:[1,0,3,2] row_mask:0xf bank_mask:0xf
	v_add_f32_dpp v91, v91, v91 quad_perm:[1,0,3,2] row_mask:0xf bank_mask:0xf
	v_add_f32_dpp v92, v92, v92 quad_perm:[1,0,3,2] row_mask:0xf bank_mask:0xf
	v_add_f32_dpp v89, v89, v89 quad_perm:[2,3,0,1] row_mask:0xf bank_mask:0xf
	v_add_f32_dpp v90, v90, v90 quad_perm:[2,3,0,1] row_mask:0xf bank_mask:0xf
	v_add_f32_dpp v91, v91, v91 quad_perm:[2,3,0,1] row_mask:0xf bank_mask:0xf
	v_add_f32_dpp v92, v92, v92 quad_perm:[2,3,0,1] row_mask:0xf bank_mask:0xf
	v_add_f32_dpp v89, v89, v89 row_half_mirror row_mask:0xf bank_mask:0xf
	v_add_f32_dpp v90, v90, v90 row_half_mirror row_mask:0xf bank_mask:0xf
	v_add_f32_dpp v91, v91, v91 row_half_mirror row_mask:0xf bank_mask:0xf
	v_add_f32_dpp v92, v92, v92 row_half_mirror row_mask:0xf bank_mask:0xf
	v_add_f32_dpp v89, v89, v89 row_mirror row_mask:0xf bank_mask:0xf
	v_add_f32_dpp v90, v90, v90 row_mirror row_mask:0xf bank_mask:0xf
	v_add_f32_dpp v91, v91, v91 row_mirror row_mask:0xf bank_mask:0xf
	v_add_f32_dpp v92, v92, v92 row_mirror row_mask:0xf bank_mask:0xf
	v_mul_f32_e32 v89, 0x3d800000, v89
	v_mul_f32_e32 v90, 0x3d800000, v90
	v_mul_f32_e32 v91, 0x3d800000, v91
	v_mul_f32_e32 v92, 0x3d800000, v92
	s_and_saveexec_b64 s[28:29], s[0:1]
	ds_write_b32 v88, v89 offset:48
	ds_write_b32 v88, v90 offset:1072
	ds_write_b32 v88, v91 offset:2096
	ds_write_b32 v88, v92 offset:3120
	s_mov_b64 exec, s[28:29]
	s_waitcnt vmcnt(12)
	v_mul_f32_e32 v89, v225, v25
	v_fmac_f32_e32 v89, v224, v24
	v_fmac_f32_e32 v89, v226, v26
	v_fmac_f32_e32 v89, v227, v27
	v_mul_f32_e32 v93, v229, v29
	v_fmac_f32_e32 v93, v228, v28
	v_fmac_f32_e32 v93, v230, v30
	v_fmac_f32_e32 v93, v231, v31
	v_add_f32_e32 v89, v89, v93
	v_mul_f32_e32 v93, v233, v33
	v_fmac_f32_e32 v93, v232, v32
	v_fmac_f32_e32 v93, v234, v34
	v_fmac_f32_e32 v93, v235, v35
	v_add_f32_e32 v89, v89, v93
	v_mul_f32_e32 v93, v237, v37
	v_fmac_f32_e32 v93, v236, v36
	v_fmac_f32_e32 v93, v238, v38
	v_fmac_f32_e32 v93, v239, v39
	v_add_f32_e32 v89, v89, v93
	v_mul_f32_e32 v90, v225, v41
	v_fmac_f32_e32 v90, v224, v40
	v_fmac_f32_e32 v90, v226, v42
	v_fmac_f32_e32 v90, v227, v43
	v_mul_f32_e32 v93, v229, v45
	v_fmac_f32_e32 v93, v228, v44
	v_fmac_f32_e32 v93, v230, v46
	v_fmac_f32_e32 v93, v231, v47
	v_add_f32_e32 v90, v90, v93
	v_mul_f32_e32 v93, v233, v49
	v_fmac_f32_e32 v93, v232, v48
	v_fmac_f32_e32 v93, v234, v50
	v_fmac_f32_e32 v93, v235, v51
	v_add_f32_e32 v90, v90, v93
	v_mul_f32_e32 v93, v237, v53
	v_fmac_f32_e32 v93, v236, v52
	v_fmac_f32_e32 v93, v238, v54
	v_fmac_f32_e32 v93, v239, v55
	v_add_f32_e32 v90, v90, v93
	v_mul_f32_e32 v91, v225, v57
	v_fmac_f32_e32 v91, v224, v56
	v_fmac_f32_e32 v91, v226, v58
	v_fmac_f32_e32 v91, v227, v59
	v_mul_f32_e32 v93, v229, v61
	v_fmac_f32_e32 v93, v228, v60
	v_fmac_f32_e32 v93, v230, v62
	v_fmac_f32_e32 v93, v231, v63
	v_add_f32_e32 v91, v91, v93
	v_mul_f32_e32 v93, v233, v65
	v_fmac_f32_e32 v93, v232, v64
	v_fmac_f32_e32 v93, v234, v66
	v_fmac_f32_e32 v93, v235, v67
	v_add_f32_e32 v91, v91, v93
	v_mul_f32_e32 v93, v237, v69
	v_fmac_f32_e32 v93, v236, v68
	v_fmac_f32_e32 v93, v238, v70
	v_fmac_f32_e32 v93, v239, v71
	v_add_f32_e32 v91, v91, v93
	v_mul_f32_e32 v92, v225, v73
	v_fmac_f32_e32 v92, v224, v72
	v_fmac_f32_e32 v92, v226, v74
	v_fmac_f32_e32 v92, v227, v75
	v_mul_f32_e32 v93, v229, v77
	v_fmac_f32_e32 v93, v228, v76
	v_fmac_f32_e32 v93, v230, v78
	v_fmac_f32_e32 v93, v231, v79
	v_add_f32_e32 v92, v92, v93
	v_mul_f32_e32 v93, v233, v81
	v_fmac_f32_e32 v93, v232, v80
	v_fmac_f32_e32 v93, v234, v82
	v_fmac_f32_e32 v93, v235, v83
	v_add_f32_e32 v92, v92, v93
	v_mul_f32_e32 v93, v237, v85
	v_fmac_f32_e32 v93, v236, v84
	v_fmac_f32_e32 v93, v238, v86
	v_fmac_f32_e32 v93, v239, v87
	v_add_f32_e32 v92, v92, v93
	v_add_f32_dpp v89, v89, v89 quad_perm:[1,0,3,2] row_mask:0xf bank_mask:0xf
	v_add_f32_dpp v90, v90, v90 quad_perm:[1,0,3,2] row_mask:0xf bank_mask:0xf
	v_add_f32_dpp v91, v91, v91 quad_perm:[1,0,3,2] row_mask:0xf bank_mask:0xf
	v_add_f32_dpp v92, v92, v92 quad_perm:[1,0,3,2] row_mask:0xf bank_mask:0xf
	v_add_f32_dpp v89, v89, v89 quad_perm:[2,3,0,1] row_mask:0xf bank_mask:0xf
	v_add_f32_dpp v90, v90, v90 quad_perm:[2,3,0,1] row_mask:0xf bank_mask:0xf
	v_add_f32_dpp v91, v91, v91 quad_perm:[2,3,0,1] row_mask:0xf bank_mask:0xf
	v_add_f32_dpp v92, v92, v92 quad_perm:[2,3,0,1] row_mask:0xf bank_mask:0xf
	v_add_f32_dpp v89, v89, v89 row_half_mirror row_mask:0xf bank_mask:0xf
	v_add_f32_dpp v90, v90, v90 row_half_mirror row_mask:0xf bank_mask:0xf
	v_add_f32_dpp v91, v91, v91 row_half_mirror row_mask:0xf bank_mask:0xf
	v_add_f32_dpp v92, v92, v92 row_half_mirror row_mask:0xf bank_mask:0xf
	v_add_f32_dpp v89, v89, v89 row_mirror row_mask:0xf bank_mask:0xf
	v_add_f32_dpp v90, v90, v90 row_mirror row_mask:0xf bank_mask:0xf
	v_add_f32_dpp v91, v91, v91 row_mirror row_mask:0xf bank_mask:0xf
	v_add_f32_dpp v92, v92, v92 row_mirror row_mask:0xf bank_mask:0xf
	v_mul_f32_e32 v89, 0x3d800000, v89
	v_mul_f32_e32 v90, 0x3d800000, v90
	v_mul_f32_e32 v91, 0x3d800000, v91
	v_mul_f32_e32 v92, 0x3d800000, v92
	s_and_saveexec_b64 s[28:29], s[0:1]
	ds_write_b32 v88, v89 offset:64
	ds_write_b32 v88, v90 offset:1088
	ds_write_b32 v88, v91 offset:2112
	ds_write_b32 v88, v92 offset:3136
	s_mov_b64 exec, s[28:29]
	s_waitcnt vmcnt(8)
	v_mul_f32_e32 v89, v241, v25
	v_fmac_f32_e32 v89, v240, v24
	v_fmac_f32_e32 v89, v242, v26
	v_fmac_f32_e32 v89, v243, v27
	v_mul_f32_e32 v93, v245, v29
	v_fmac_f32_e32 v93, v244, v28
	v_fmac_f32_e32 v93, v246, v30
	v_fmac_f32_e32 v93, v247, v31
	v_add_f32_e32 v89, v89, v93
	v_mul_f32_e32 v93, v249, v33
	v_fmac_f32_e32 v93, v248, v32
	v_fmac_f32_e32 v93, v250, v34
	v_fmac_f32_e32 v93, v251, v35
	v_add_f32_e32 v89, v89, v93
	v_mul_f32_e32 v93, v129, v37
	v_fmac_f32_e32 v93, v128, v36
	v_fmac_f32_e32 v93, v130, v38
	v_fmac_f32_e32 v93, v131, v39
	v_add_f32_e32 v89, v89, v93
	v_mul_f32_e32 v90, v241, v41
	v_fmac_f32_e32 v90, v240, v40
	v_fmac_f32_e32 v90, v242, v42
	v_fmac_f32_e32 v90, v243, v43
	v_mul_f32_e32 v93, v245, v45
	v_fmac_f32_e32 v93, v244, v44
	v_fmac_f32_e32 v93, v246, v46
	v_fmac_f32_e32 v93, v247, v47
	v_add_f32_e32 v90, v90, v93
	v_mul_f32_e32 v93, v249, v49
	v_fmac_f32_e32 v93, v248, v48
	v_fmac_f32_e32 v93, v250, v50
	v_fmac_f32_e32 v93, v251, v51
	v_add_f32_e32 v90, v90, v93
	v_mul_f32_e32 v93, v129, v53
	v_fmac_f32_e32 v93, v128, v52
	v_fmac_f32_e32 v93, v130, v54
	v_fmac_f32_e32 v93, v131, v55
	v_add_f32_e32 v90, v90, v93
	v_mul_f32_e32 v91, v241, v57
	v_fmac_f32_e32 v91, v240, v56
	v_fmac_f32_e32 v91, v242, v58
	v_fmac_f32_e32 v91, v243, v59
	v_mul_f32_e32 v93, v245, v61
	v_fmac_f32_e32 v93, v244, v60
	v_fmac_f32_e32 v93, v246, v62
	v_fmac_f32_e32 v93, v247, v63
	v_add_f32_e32 v91, v91, v93
	v_mul_f32_e32 v93, v249, v65
	v_fmac_f32_e32 v93, v248, v64
	v_fmac_f32_e32 v93, v250, v66
	v_fmac_f32_e32 v93, v251, v67
	v_add_f32_e32 v91, v91, v93
	v_mul_f32_e32 v93, v129, v69
	v_fmac_f32_e32 v93, v128, v68
	v_fmac_f32_e32 v93, v130, v70
	v_fmac_f32_e32 v93, v131, v71
	v_add_f32_e32 v91, v91, v93
	v_mul_f32_e32 v92, v241, v73
	v_fmac_f32_e32 v92, v240, v72
	v_fmac_f32_e32 v92, v242, v74
	v_fmac_f32_e32 v92, v243, v75
	v_mul_f32_e32 v93, v245, v77
	v_fmac_f32_e32 v93, v244, v76
	v_fmac_f32_e32 v93, v246, v78
	v_fmac_f32_e32 v93, v247, v79
	v_add_f32_e32 v92, v92, v93
	v_mul_f32_e32 v93, v249, v81
	v_fmac_f32_e32 v93, v248, v80
	v_fmac_f32_e32 v93, v250, v82
	v_fmac_f32_e32 v93, v251, v83
	v_add_f32_e32 v92, v92, v93
	v_mul_f32_e32 v93, v129, v85
	v_fmac_f32_e32 v93, v128, v84
	v_fmac_f32_e32 v93, v130, v86
	v_fmac_f32_e32 v93, v131, v87
	v_add_f32_e32 v92, v92, v93
	v_add_f32_dpp v89, v89, v89 quad_perm:[1,0,3,2] row_mask:0xf bank_mask:0xf
	v_add_f32_dpp v90, v90, v90 quad_perm:[1,0,3,2] row_mask:0xf bank_mask:0xf
	v_add_f32_dpp v91, v91, v91 quad_perm:[1,0,3,2] row_mask:0xf bank_mask:0xf
	v_add_f32_dpp v92, v92, v92 quad_perm:[1,0,3,2] row_mask:0xf bank_mask:0xf
	v_add_f32_dpp v89, v89, v89 quad_perm:[2,3,0,1] row_mask:0xf bank_mask:0xf
	v_add_f32_dpp v90, v90, v90 quad_perm:[2,3,0,1] row_mask:0xf bank_mask:0xf
	v_add_f32_dpp v91, v91, v91 quad_perm:[2,3,0,1] row_mask:0xf bank_mask:0xf
	v_add_f32_dpp v92, v92, v92 quad_perm:[2,3,0,1] row_mask:0xf bank_mask:0xf
	v_add_f32_dpp v89, v89, v89 row_half_mirror row_mask:0xf bank_mask:0xf
	v_add_f32_dpp v90, v90, v90 row_half_mirror row_mask:0xf bank_mask:0xf
	v_add_f32_dpp v91, v91, v91 row_half_mirror row_mask:0xf bank_mask:0xf
	v_add_f32_dpp v92, v92, v92 row_half_mirror row_mask:0xf bank_mask:0xf
	v_add_f32_dpp v89, v89, v89 row_mirror row_mask:0xf bank_mask:0xf
	v_add_f32_dpp v90, v90, v90 row_mirror row_mask:0xf bank_mask:0xf
	v_add_f32_dpp v91, v91, v91 row_mirror row_mask:0xf bank_mask:0xf
	v_add_f32_dpp v92, v92, v92 row_mirror row_mask:0xf bank_mask:0xf
	v_mul_f32_e32 v89, 0x3d800000, v89
	v_mul_f32_e32 v90, 0x3d800000, v90
	v_mul_f32_e32 v91, 0x3d800000, v91
	v_mul_f32_e32 v92, 0x3d800000, v92
	s_and_saveexec_b64 s[28:29], s[0:1]
	ds_write_b32 v88, v89 offset:80
	ds_write_b32 v88, v90 offset:1104
	ds_write_b32 v88, v91 offset:2128
	ds_write_b32 v88, v92 offset:3152
	s_mov_b64 exec, s[28:29]
	s_waitcnt vmcnt(4)
	v_mul_f32_e32 v89, v1, v25
	v_fmac_f32_e32 v89, v0, v24
	v_fmac_f32_e32 v89, v2, v26
	v_fmac_f32_e32 v89, v3, v27
	v_mul_f32_e32 v93, v5, v29
	v_fmac_f32_e32 v93, v4, v28
	v_fmac_f32_e32 v93, v6, v30
	v_fmac_f32_e32 v93, v7, v31
	v_add_f32_e32 v89, v89, v93
	v_mul_f32_e32 v93, v9, v33
	v_fmac_f32_e32 v93, v8, v32
	v_fmac_f32_e32 v93, v10, v34
	v_fmac_f32_e32 v93, v11, v35
	v_add_f32_e32 v89, v89, v93
	v_mul_f32_e32 v93, v13, v37
	v_fmac_f32_e32 v93, v12, v36
	v_fmac_f32_e32 v93, v14, v38
	v_fmac_f32_e32 v93, v15, v39
	v_add_f32_e32 v89, v89, v93
	v_mul_f32_e32 v90, v1, v41
	v_fmac_f32_e32 v90, v0, v40
	v_fmac_f32_e32 v90, v2, v42
	v_fmac_f32_e32 v90, v3, v43
	v_mul_f32_e32 v93, v5, v45
	v_fmac_f32_e32 v93, v4, v44
	v_fmac_f32_e32 v93, v6, v46
	v_fmac_f32_e32 v93, v7, v47
	v_add_f32_e32 v90, v90, v93
	v_mul_f32_e32 v93, v9, v49
	v_fmac_f32_e32 v93, v8, v48
	v_fmac_f32_e32 v93, v10, v50
	v_fmac_f32_e32 v93, v11, v51
	v_add_f32_e32 v90, v90, v93
	v_mul_f32_e32 v93, v13, v53
	v_fmac_f32_e32 v93, v12, v52
	v_fmac_f32_e32 v93, v14, v54
	v_fmac_f32_e32 v93, v15, v55
	v_add_f32_e32 v90, v90, v93
	v_mul_f32_e32 v91, v1, v57
	v_fmac_f32_e32 v91, v0, v56
	v_fmac_f32_e32 v91, v2, v58
	v_fmac_f32_e32 v91, v3, v59
	v_mul_f32_e32 v93, v5, v61
	v_fmac_f32_e32 v93, v4, v60
	v_fmac_f32_e32 v93, v6, v62
	v_fmac_f32_e32 v93, v7, v63
	v_add_f32_e32 v91, v91, v93
	v_mul_f32_e32 v93, v9, v65
	v_fmac_f32_e32 v93, v8, v64
	v_fmac_f32_e32 v93, v10, v66
	v_fmac_f32_e32 v93, v11, v67
	v_add_f32_e32 v91, v91, v93
	v_mul_f32_e32 v93, v13, v69
	v_fmac_f32_e32 v93, v12, v68
	v_fmac_f32_e32 v93, v14, v70
	v_fmac_f32_e32 v93, v15, v71
	v_add_f32_e32 v91, v91, v93
	v_mul_f32_e32 v92, v1, v73
	v_fmac_f32_e32 v92, v0, v72
	v_fmac_f32_e32 v92, v2, v74
	v_fmac_f32_e32 v92, v3, v75
	v_mul_f32_e32 v93, v5, v77
	v_fmac_f32_e32 v93, v4, v76
	v_fmac_f32_e32 v93, v6, v78
	v_fmac_f32_e32 v93, v7, v79
	v_add_f32_e32 v92, v92, v93
	v_mul_f32_e32 v93, v9, v81
	v_fmac_f32_e32 v93, v8, v80
	v_fmac_f32_e32 v93, v10, v82
	v_fmac_f32_e32 v93, v11, v83
	v_add_f32_e32 v92, v92, v93
	v_mul_f32_e32 v93, v13, v85
	v_fmac_f32_e32 v93, v12, v84
	v_fmac_f32_e32 v93, v14, v86
	v_fmac_f32_e32 v93, v15, v87
	v_add_f32_e32 v92, v92, v93
	v_add_f32_dpp v89, v89, v89 quad_perm:[1,0,3,2] row_mask:0xf bank_mask:0xf
	v_add_f32_dpp v90, v90, v90 quad_perm:[1,0,3,2] row_mask:0xf bank_mask:0xf
	v_add_f32_dpp v91, v91, v91 quad_perm:[1,0,3,2] row_mask:0xf bank_mask:0xf
	v_add_f32_dpp v92, v92, v92 quad_perm:[1,0,3,2] row_mask:0xf bank_mask:0xf
	v_add_f32_dpp v89, v89, v89 quad_perm:[2,3,0,1] row_mask:0xf bank_mask:0xf
	v_add_f32_dpp v90, v90, v90 quad_perm:[2,3,0,1] row_mask:0xf bank_mask:0xf
	v_add_f32_dpp v91, v91, v91 quad_perm:[2,3,0,1] row_mask:0xf bank_mask:0xf
	v_add_f32_dpp v92, v92, v92 quad_perm:[2,3,0,1] row_mask:0xf bank_mask:0xf
	v_add_f32_dpp v89, v89, v89 row_half_mirror row_mask:0xf bank_mask:0xf
	v_add_f32_dpp v90, v90, v90 row_half_mirror row_mask:0xf bank_mask:0xf
	v_add_f32_dpp v91, v91, v91 row_half_mirror row_mask:0xf bank_mask:0xf
	v_add_f32_dpp v92, v92, v92 row_half_mirror row_mask:0xf bank_mask:0xf
	v_add_f32_dpp v89, v89, v89 row_mirror row_mask:0xf bank_mask:0xf
	v_add_f32_dpp v90, v90, v90 row_mirror row_mask:0xf bank_mask:0xf
	v_add_f32_dpp v91, v91, v91 row_mirror row_mask:0xf bank_mask:0xf
	v_add_f32_dpp v92, v92, v92 row_mirror row_mask:0xf bank_mask:0xf
	v_mul_f32_e32 v89, 0x3d800000, v89
	v_mul_f32_e32 v90, 0x3d800000, v90
	v_mul_f32_e32 v91, 0x3d800000, v91
	v_mul_f32_e32 v92, 0x3d800000, v92
	s_and_saveexec_b64 s[28:29], s[0:1]
	ds_write_b32 v88, v89 offset:96
	ds_write_b32 v88, v90 offset:1120
	ds_write_b32 v88, v91 offset:2144
	ds_write_b32 v88, v92 offset:3168
	s_mov_b64 exec, s[28:29]
	s_waitcnt vmcnt(0)
	v_mul_f32_e32 v89, v97, v25
	v_fmac_f32_e32 v89, v96, v24
	v_fmac_f32_e32 v89, v98, v26
	v_fmac_f32_e32 v89, v99, v27
	v_mul_f32_e32 v93, v101, v29
	v_fmac_f32_e32 v93, v100, v28
	v_fmac_f32_e32 v93, v102, v30
	v_fmac_f32_e32 v93, v103, v31
	v_add_f32_e32 v89, v89, v93
	v_mul_f32_e32 v93, v105, v33
	v_fmac_f32_e32 v93, v104, v32
	v_fmac_f32_e32 v93, v106, v34
	v_fmac_f32_e32 v93, v107, v35
	v_add_f32_e32 v89, v89, v93
	v_mul_f32_e32 v93, v109, v37
	v_fmac_f32_e32 v93, v108, v36
	v_fmac_f32_e32 v93, v110, v38
	v_fmac_f32_e32 v93, v111, v39
	v_add_f32_e32 v89, v89, v93
	v_mul_f32_e32 v90, v97, v41
	v_fmac_f32_e32 v90, v96, v40
	v_fmac_f32_e32 v90, v98, v42
	v_fmac_f32_e32 v90, v99, v43
	v_mul_f32_e32 v93, v101, v45
	v_fmac_f32_e32 v93, v100, v44
	v_fmac_f32_e32 v93, v102, v46
	v_fmac_f32_e32 v93, v103, v47
	v_add_f32_e32 v90, v90, v93
	v_mul_f32_e32 v93, v105, v49
	v_fmac_f32_e32 v93, v104, v48
	v_fmac_f32_e32 v93, v106, v50
	v_fmac_f32_e32 v93, v107, v51
	v_add_f32_e32 v90, v90, v93
	v_mul_f32_e32 v93, v109, v53
	v_fmac_f32_e32 v93, v108, v52
	v_fmac_f32_e32 v93, v110, v54
	v_fmac_f32_e32 v93, v111, v55
	v_add_f32_e32 v90, v90, v93
	v_mul_f32_e32 v91, v97, v57
	v_fmac_f32_e32 v91, v96, v56
	v_fmac_f32_e32 v91, v98, v58
	v_fmac_f32_e32 v91, v99, v59
	v_mul_f32_e32 v93, v101, v61
	v_fmac_f32_e32 v93, v100, v60
	v_fmac_f32_e32 v93, v102, v62
	v_fmac_f32_e32 v93, v103, v63
	v_add_f32_e32 v91, v91, v93
	v_mul_f32_e32 v93, v105, v65
	v_fmac_f32_e32 v93, v104, v64
	v_fmac_f32_e32 v93, v106, v66
	v_fmac_f32_e32 v93, v107, v67
	v_add_f32_e32 v91, v91, v93
	v_mul_f32_e32 v93, v109, v69
	v_fmac_f32_e32 v93, v108, v68
	v_fmac_f32_e32 v93, v110, v70
	v_fmac_f32_e32 v93, v111, v71
	v_add_f32_e32 v91, v91, v93
	v_mul_f32_e32 v92, v97, v73
	v_fmac_f32_e32 v92, v96, v72
	v_fmac_f32_e32 v92, v98, v74
	v_fmac_f32_e32 v92, v99, v75
	v_mul_f32_e32 v93, v101, v77
	v_fmac_f32_e32 v93, v100, v76
	v_fmac_f32_e32 v93, v102, v78
	v_fmac_f32_e32 v93, v103, v79
	v_add_f32_e32 v92, v92, v93
	v_mul_f32_e32 v93, v105, v81
	v_fmac_f32_e32 v93, v104, v80
	v_fmac_f32_e32 v93, v106, v82
	v_fmac_f32_e32 v93, v107, v83
	v_add_f32_e32 v92, v92, v93
	v_mul_f32_e32 v93, v109, v85
	v_fmac_f32_e32 v93, v108, v84
	v_fmac_f32_e32 v93, v110, v86
	v_fmac_f32_e32 v93, v111, v87
	v_add_f32_e32 v92, v92, v93
	v_add_f32_dpp v89, v89, v89 quad_perm:[1,0,3,2] row_mask:0xf bank_mask:0xf
	v_add_f32_dpp v90, v90, v90 quad_perm:[1,0,3,2] row_mask:0xf bank_mask:0xf
	v_add_f32_dpp v91, v91, v91 quad_perm:[1,0,3,2] row_mask:0xf bank_mask:0xf
	v_add_f32_dpp v92, v92, v92 quad_perm:[1,0,3,2] row_mask:0xf bank_mask:0xf
	v_add_f32_dpp v89, v89, v89 quad_perm:[2,3,0,1] row_mask:0xf bank_mask:0xf
	v_add_f32_dpp v90, v90, v90 quad_perm:[2,3,0,1] row_mask:0xf bank_mask:0xf
	v_add_f32_dpp v91, v91, v91 quad_perm:[2,3,0,1] row_mask:0xf bank_mask:0xf
	v_add_f32_dpp v92, v92, v92 quad_perm:[2,3,0,1] row_mask:0xf bank_mask:0xf
	v_add_f32_dpp v89, v89, v89 row_half_mirror row_mask:0xf bank_mask:0xf
	v_add_f32_dpp v90, v90, v90 row_half_mirror row_mask:0xf bank_mask:0xf
	v_add_f32_dpp v91, v91, v91 row_half_mirror row_mask:0xf bank_mask:0xf
	v_add_f32_dpp v92, v92, v92 row_half_mirror row_mask:0xf bank_mask:0xf
	v_add_f32_dpp v89, v89, v89 row_mirror row_mask:0xf bank_mask:0xf
	v_add_f32_dpp v90, v90, v90 row_mirror row_mask:0xf bank_mask:0xf
	v_add_f32_dpp v91, v91, v91 row_mirror row_mask:0xf bank_mask:0xf
	v_add_f32_dpp v92, v92, v92 row_mirror row_mask:0xf bank_mask:0xf
	v_mul_f32_e32 v89, 0x3d800000, v89
	v_mul_f32_e32 v90, 0x3d800000, v90
	v_mul_f32_e32 v91, 0x3d800000, v91
	v_mul_f32_e32 v92, 0x3d800000, v92
	s_and_saveexec_b64 s[28:29], s[0:1]
	ds_write_b32 v88, v89 offset:112
	ds_write_b32 v88, v90 offset:1136
	ds_write_b32 v88, v91 offset:2160
	ds_write_b32 v88, v92 offset:3184
	s_mov_b64 exec, s[28:29]
